# NSA selected-block loop: per-score bias is one fma against a per-unit sl2*(ci+4h) table; the per-tile base is added to the row max and folded into the softmax subtrahend
# baseline (speedup 1.0000x reference)
.LBB0_1428:
	v_readfirstlane_b32 s52, v138
	s_lshl_b32 s24, s42, 1
	s_add_u32 s24, s22, s24
	s_addc_u32 s25, s23, 0
	v_ashrrev_i32_e32 v250, 3, v214
	v_add_u32_e32 v236, s96, v250
	v_ashrrev_i32_e32 v237, 31, v236
	v_lshlrev_b64 v[236:237], 12, v[236:237]
	v_lshlrev_b32_e32 v238, 4, v214
	v_and_b32_e32 v238, 0x70, v238
	v_mov_b32_e32 v239, 0
	v_lshl_add_u64 v[236:237], s[24:25], 0, v[236:237]
	v_lshl_add_u64 v[236:237], v[236:237], 0, v[238:239]
	v_and_b32_e32 v248, 63, v214
	v_or_b32_e32 v248, s96, v248
	v_lshlrev_b32_e32 v248, 12, v248
	v_mov_b32_e32 v249, 0
	v_and_b32_e32 v250, -8, v250
	v_lshlrev_b32_e32 v250, 1, v250
	v_mov_b32_e32 v251, 0
	v_lshl_add_u64 v[248:249], s[24:25], 0, v[248:249]
	v_lshl_add_u64 v[248:249], v[248:249], 0, v[250:251]
	global_load_dwordx4 v[240:243], v[236:237], off offset:3072
	global_load_dwordx4 v[244:247], v[248:249], off offset:3840
	v_cvt_f32_i32_e32 v140, v139
	v_mul_f32_e32 v140, v186, v140
	v_fmamk_f32 v160, v186, 0x3f800000, v140
	v_fmamk_f32 v170, v186, 0x40000000, v140
	v_fmamk_f32 v171, v186, 0x40400000, v140
	v_fmamk_f32 v176, v186, 0x41000000, v140
	v_fmamk_f32 v177, v186, 0x41100000, v140
	v_fmamk_f32 v187, v186, 0x41200000, v140
	v_fmamk_f32 v188, v186, 0x41300000, v140
	v_fmamk_f32 v189, v186, 0x41800000, v140
	v_fmamk_f32 v190, v186, 0x41880000, v140
	v_fmamk_f32 v191, v186, 0x41900000, v140
	v_fmamk_f32 v192, v186, 0x41980000, v140
	v_fmamk_f32 v193, v186, 0x41c00000, v140
	v_fmamk_f32 v194, v186, 0x41c80000, v140
	v_fmamk_f32 v195, v186, 0x41d00000, v140
	v_fmamk_f32 v196, v186, 0x41d80000, v140
	v_fmamk_f32 v197, v186, 0x42000000, v140
	v_fmamk_f32 v198, v186, 0x42040000, v140
	v_fmamk_f32 v199, v186, 0x42080000, v140
	v_fmamk_f32 v207, v186, 0x420c0000, v140
	v_fmamk_f32 v210, v186, 0x42200000, v140
	v_fmamk_f32 v211, v186, 0x42240000, v140
	v_fmamk_f32 v212, v186, 0x42280000, v140
	v_fmamk_f32 v213, v186, 0x422c0000, v140
	v_fmamk_f32 v233, v186, 0x42400000, v140
	v_fmamk_f32 v234, v186, 0x42440000, v140
	v_fmamk_f32 v235, v186, 0x42480000, v140
	v_fmamk_f32 v236, v186, 0x424c0000, v140
	v_fmamk_f32 v237, v186, 0x42600000, v140
	v_fmamk_f32 v238, v186, 0x42640000, v140
	v_fmamk_f32 v239, v186, 0x42680000, v140
	v_fmamk_f32 v248, v186, 0x426c0000, v140

.Lsel_nn0:
	s_cmp_lt_i32 s17, 0
	s_cselect_b32 s24, s43, s17
	v_add_u32_e32 v6, s24, v136
	v_add_u32_e32 v2, s24, v137
	v_lshlrev_b32_e32 v6, 12, v6
	v_lshlrev_b32_e32 v2, 12, v2
	v_mov_b32_e32 v7, v1
	v_mov_b32_e32 v3, v1
	v_lshl_add_u64 v[6:7], v[122:123], 0, v[6:7]
	v_lshl_add_u64 v[2:3], v[124:125], 0, v[2:3]
	global_load_dwordx4 v[6:9], v[6:7], off offset:2816
	global_load_dwordx4 v[2:5], v[2:3], off offset:3584
	s_lshr_b32 s24, s43, 6
	v_lshrrev_b64 v[14:15], s24, v[120:121]
	v_and_b32_e32 v14, 1, v14
	v_cmp_eq_u32_e32 vcc, 1, v14
	s_cbranch_vccz .Lsel_skip0
	ds_read_b128 v[126:129], v161 offset:0
	ds_read_b128 v[130:133], v161 offset:4608
	ds_read_b128 v[164:167], v161 offset:32
	ds_read_b128 v[10:13], v161 offset:4640
	s_waitcnt lgkmcnt(3)
	v_mfma_f32_32x32x16_bf16 v[96:111], v[126:129], v[144:147], 0
	ds_read_b128 v[126:129], v161 offset:64
	s_waitcnt lgkmcnt(3)
	v_mfma_f32_32x32x16_bf16 v[80:95], v[130:133], v[144:147], 0
	ds_read_b128 v[130:133], v161 offset:4672
	s_waitcnt lgkmcnt(3)
	v_mfma_f32_32x32x16_bf16 v[96:111], v[164:167], v[148:151], v[96:111]
	ds_read_b128 v[164:167], v161 offset:96
	s_waitcnt lgkmcnt(3)
	v_mfma_f32_32x32x16_bf16 v[80:95], v[10:13], v[148:151], v[80:95]
	ds_read_b128 v[10:13], v161 offset:4704
	s_waitcnt lgkmcnt(3)
	v_mfma_f32_32x32x16_bf16 v[96:111], v[126:129], v[152:155], v[96:111]
	s_waitcnt lgkmcnt(2)
	v_mfma_f32_32x32x16_bf16 v[80:95], v[130:133], v[152:155], v[80:95]
	s_waitcnt lgkmcnt(1)
	v_mfma_f32_32x32x16_bf16 v[96:111], v[164:167], v[156:159], v[96:111]
	s_waitcnt lgkmcnt(0)
	v_mfma_f32_32x32x16_bf16 v[80:95], v[10:13], v[156:159], v[80:95]
	v_sub_u32_e32 v163, s43, v205
	v_cvt_f32_i32_e32 v163, v163
	v_mul_f32_e32 v134, v186, v163
	v_cndmask_b32_e32 v134, v225, v134, vcc
	s_nop 7
	v_fma_f32 v96, v96, s84, v140
	v_fma_f32 v97, v97, s84, v160
	v_fma_f32 v98, v98, s84, v170
	v_fma_f32 v99, v99, s84, v171
	v_fma_f32 v100, v100, s84, v176
	v_fma_f32 v101, v101, s84, v177
	v_fma_f32 v102, v102, s84, v187
	v_fma_f32 v103, v103, s84, v188
	v_fma_f32 v104, v104, s84, v189
	v_fma_f32 v105, v105, s84, v190
	v_fma_f32 v106, v106, s84, v191
	v_fma_f32 v107, v107, s84, v192
	v_fma_f32 v108, v108, s84, v193
	v_fma_f32 v109, v109, s84, v194
	v_fma_f32 v110, v110, s84, v195
	v_fma_f32 v111, v111, s84, v196
	v_fma_f32 v80, v80, s84, v197
	v_fma_f32 v81, v81, s84, v198
	v_fma_f32 v82, v82, s84, v199
	v_fma_f32 v83, v83, s84, v207
	v_fma_f32 v84, v84, s84, v210
	v_fma_f32 v85, v85, s84, v211
	v_fma_f32 v86, v86, s84, v212
	v_fma_f32 v87, v87, s84, v213
	v_fma_f32 v88, v88, s84, v233
	v_fma_f32 v89, v89, s84, v234
	v_fma_f32 v90, v90, s84, v235
	v_fma_f32 v91, v91, s84, v236
	v_fma_f32 v92, v92, s84, v237
	v_fma_f32 v93, v93, s84, v238
	v_fma_f32 v94, v94, s84, v239
	v_fma_f32 v95, v95, s84, v248
	s_add_i32 s24, s43, 63
	s_cmp_gt_i32 s24, s52
	s_cbranch_scc1 .Lsel_mask0
; template <bool PV> DI void online_step_mx(f32x16& x0, f32x16& x1, float mx, float& m, float& l, f32x16 (&O)[2]) {
;     const float mn = fmaxf(m, mx), alpha = __builtin_amdgcn_exp2f(m - mn);
;     float ls = 0.f;
; #pragma unroll
;     for (int i = 0; i < 16; ++i) { x0[i] = __builtin_amdgcn_exp2f(x0[i] - mn); x1[i] = __builtin_amdgcn_exp2f(x1[i] - mn); ls += x0[i] + x1[i]; }
;     ls += __shfl_xor(ls, 32);
;     l = l * alpha + ls; m = mn;
;     if (PV) { if (__any(alpha != 1.f)) {
; #pragma unroll
;         for (int i = 0; i < 16; ++i) { O[0][i] *= alpha; O[1][i] *= alpha; } } }
.Lsel_mdone0:
	v_max3_f32 v0, v96, v97, v98
	v_max3_f32 v163, v99, v100, v101
	v_max3_f32 v0, v0, v102, v103
	v_max3_f32 v163, v163, v104, v105
	v_max3_f32 v0, v0, v106, v107
	v_max3_f32 v163, v163, v108, v109
	v_max3_f32 v0, v0, v110, v111
	v_max3_f32 v163, v163, v80, v81
	v_max3_f32 v0, v0, v82, v83
	v_max3_f32 v163, v163, v84, v85
	v_max3_f32 v0, v0, v86, v87
	v_max3_f32 v163, v163, v88, v89
	v_max3_f32 v0, v0, v90, v91
	v_max3_f32 v163, v163, v92, v93
	v_max3_f32 v0, v0, v94, v95
	v_max_f32_e32 v0, v0, v163
	v_mov_b32_e32 v163, v0
	s_nop 1
	v_permlane32_swap_b32_e32 v163, v0
	v_max_f32_e32 v0, v0, v163
	v_add_f32_e32 v0, v0, v134
	v_sub_f32_e32 v163, v0, v162
	v_cmp_lt_f32_e32 vcc, s87, v163
	s_cbranch_vccz .Lsel_skip0
	v_max_f32_e32 v163, v162, v0
	v_sub_f32_e32 v135, v163, v134
	v_sub_f32_e32 v96, v96, v135
	v_sub_f32_e32 v97, v97, v135
	v_sub_f32_e32 v98, v98, v135
	v_sub_f32_e32 v99, v99, v135
	v_sub_f32_e32 v100, v100, v135
	v_sub_f32_e32 v101, v101, v135
	v_sub_f32_e32 v102, v102, v135
	v_sub_f32_e32 v103, v103, v135
	v_exp_f32_e32 v96, v96
	v_exp_f32_e32 v97, v97
	v_exp_f32_e32 v98, v98
	v_exp_f32_e32 v99, v99
	v_exp_f32_e32 v100, v100
	v_exp_f32_e32 v101, v101
	v_exp_f32_e32 v102, v102
	v_exp_f32_e32 v103, v103
	v_add_f32_e32 v14, v96, v98
	v_add_f32_e32 v15, v97, v99
	v_add_f32_e32 v14, v14, v100
	v_add_f32_e32 v15, v15, v101
	v_add_f32_e32 v14, v14, v102
	v_add_f32_e32 v15, v15, v103
	v_cvt_pk_bf16_f32 v96, v96, v97
	v_cvt_pk_bf16_f32 v97, v98, v99
	v_cvt_pk_bf16_f32 v98, v100, v101
	v_cvt_pk_bf16_f32 v99, v102, v103
	v_sub_f32_e32 v104, v104, v135
	v_sub_f32_e32 v105, v105, v135
	v_sub_f32_e32 v106, v106, v135
	v_sub_f32_e32 v107, v107, v135
	v_sub_f32_e32 v108, v108, v135
	v_sub_f32_e32 v109, v109, v135
	v_sub_f32_e32 v110, v110, v135
	v_sub_f32_e32 v111, v111, v135
	v_exp_f32_e32 v104, v104
	v_exp_f32_e32 v105, v105
	v_exp_f32_e32 v106, v106
	v_exp_f32_e32 v107, v107
	v_exp_f32_e32 v108, v108
	v_exp_f32_e32 v109, v109
	v_exp_f32_e32 v110, v110
	v_exp_f32_e32 v111, v111
	v_add_f32_e32 v14, v14, v104
	v_add_f32_e32 v15, v15, v105
	v_add_f32_e32 v14, v14, v106
	v_add_f32_e32 v15, v15, v107
	v_add_f32_e32 v14, v14, v108
	v_add_f32_e32 v15, v15, v109
	v_add_f32_e32 v14, v14, v110
	v_add_f32_e32 v15, v15, v111
	v_cvt_pk_bf16_f32 v104, v104, v105
	v_cvt_pk_bf16_f32 v105, v106, v107
	v_cvt_pk_bf16_f32 v106, v108, v109
	v_cvt_pk_bf16_f32 v107, v110, v111
	v_sub_f32_e32 v80, v80, v135
	v_sub_f32_e32 v81, v81, v135
	v_sub_f32_e32 v82, v82, v135
	v_sub_f32_e32 v83, v83, v135
	v_sub_f32_e32 v84, v84, v135
	v_sub_f32_e32 v85, v85, v135
	v_sub_f32_e32 v86, v86, v135
	v_sub_f32_e32 v87, v87, v135
	v_exp_f32_e32 v80, v80
	v_exp_f32_e32 v81, v81
	v_exp_f32_e32 v82, v82
	v_exp_f32_e32 v83, v83
	v_exp_f32_e32 v84, v84
	v_exp_f32_e32 v85, v85
	v_exp_f32_e32 v86, v86
	v_exp_f32_e32 v87, v87
	v_add_f32_e32 v14, v14, v80
	v_add_f32_e32 v15, v15, v81
	v_add_f32_e32 v14, v14, v82
	v_add_f32_e32 v15, v15, v83
	v_add_f32_e32 v14, v14, v84
	v_add_f32_e32 v15, v15, v85
	v_add_f32_e32 v14, v14, v86
	v_add_f32_e32 v15, v15, v87
	v_cvt_pk_bf16_f32 v80, v80, v81
	v_cvt_pk_bf16_f32 v81, v82, v83
	v_cvt_pk_bf16_f32 v82, v84, v85
	v_cvt_pk_bf16_f32 v83, v86, v87
	v_sub_f32_e32 v88, v88, v135
	v_sub_f32_e32 v89, v89, v135
	v_sub_f32_e32 v90, v90, v135
	v_sub_f32_e32 v91, v91, v135
	v_sub_f32_e32 v92, v92, v135
	v_sub_f32_e32 v93, v93, v135
	v_sub_f32_e32 v94, v94, v135
	v_sub_f32_e32 v95, v95, v135
	v_exp_f32_e32 v88, v88
	v_exp_f32_e32 v89, v89
	v_exp_f32_e32 v90, v90
	v_exp_f32_e32 v91, v91
	v_exp_f32_e32 v92, v92
	v_exp_f32_e32 v93, v93
	v_exp_f32_e32 v94, v94
	v_exp_f32_e32 v95, v95
	v_add_f32_e32 v14, v14, v88
	v_add_f32_e32 v15, v15, v89
	v_add_f32_e32 v14, v14, v90
	v_add_f32_e32 v15, v15, v91
	v_add_f32_e32 v14, v14, v92
	v_add_f32_e32 v15, v15, v93
	v_add_f32_e32 v14, v14, v94
	v_add_f32_e32 v15, v15, v95
	v_cvt_pk_bf16_f32 v88, v88, v89
	v_cvt_pk_bf16_f32 v89, v90, v91
	v_cvt_pk_bf16_f32 v90, v92, v93
	v_cvt_pk_bf16_f32 v91, v94, v95
	v_add_f32_e32 v14, v14, v15
	v_sub_f32_e32 v0, v162, v163
	v_mov_b32_e32 v15, v14
	v_exp_f32_e32 v0, v0
	s_nop 0
	v_permlane32_swap_b32_e32 v15, v14
	v_add_f32_e32 v14, v14, v15
	v_mov_b32_e32 v162, v163
	v_fmac_f32_e32 v14, v209, v0
	v_cmp_neq_f32_e32 vcc, 1.0, v0
	v_mov_b32_e32 v209, v14
	s_cbranch_vccz .Lsel_nors0
	s_nop 3
	v_mul_f32_e32 v48, v48, v0
	v_mul_f32_e32 v49, v49, v0
	v_mul_f32_e32 v50, v50, v0
	v_mul_f32_e32 v51, v51, v0
	v_mul_f32_e32 v52, v52, v0
	v_mul_f32_e32 v53, v53, v0
	v_mul_f32_e32 v54, v54, v0
	v_mul_f32_e32 v55, v55, v0
	v_mul_f32_e32 v56, v56, v0
	v_mul_f32_e32 v57, v57, v0
	v_mul_f32_e32 v58, v58, v0
	v_mul_f32_e32 v59, v59, v0
	v_mul_f32_e32 v60, v60, v0
	v_mul_f32_e32 v61, v61, v0
	v_mul_f32_e32 v62, v62, v0
	v_mul_f32_e32 v63, v63, v0
	v_mul_f32_e32 v64, v64, v0
	v_mul_f32_e32 v65, v65, v0
	v_mul_f32_e32 v66, v66, v0
	v_mul_f32_e32 v67, v67, v0
	v_mul_f32_e32 v68, v68, v0
	v_mul_f32_e32 v69, v69, v0
	v_mul_f32_e32 v70, v70, v0
	v_mul_f32_e32 v71, v71, v0
	v_mul_f32_e32 v72, v72, v0
	v_mul_f32_e32 v73, v73, v0
	v_mul_f32_e32 v74, v74, v0
	v_mul_f32_e32 v75, v75, v0
	v_mul_f32_e32 v76, v76, v0
	v_mul_f32_e32 v77, v77, v0
	v_mul_f32_e32 v78, v78, v0
	v_mul_f32_e32 v79, v79, v0

.Lsel_nn1:
	s_cmp_lt_i32 s17, 0
	s_cselect_b32 s24, s43, s17
	v_add_u32_e32 v116, s24, v136
	v_add_u32_e32 v112, s24, v137
	v_lshlrev_b32_e32 v116, 12, v116
	v_lshlrev_b32_e32 v112, 12, v112
	v_mov_b32_e32 v117, v1
	v_mov_b32_e32 v113, v1
	v_lshl_add_u64 v[116:117], v[122:123], 0, v[116:117]
	v_lshl_add_u64 v[112:113], v[124:125], 0, v[112:113]
	global_load_dwordx4 v[116:119], v[116:117], off offset:2816
	global_load_dwordx4 v[112:115], v[112:113], off offset:3584
	s_lshr_b32 s24, s43, 6
	v_lshrrev_b64 v[14:15], s24, v[120:121]
	v_and_b32_e32 v14, 1, v14
	v_cmp_eq_u32_e32 vcc, 1, v14
	s_cbranch_vccz .Lsel_skip1
	ds_read_b128 v[126:129], v161 offset:13312
	ds_read_b128 v[130:133], v161 offset:17920
	ds_read_b128 v[164:167], v161 offset:13344
	ds_read_b128 v[10:13], v161 offset:17952
	s_waitcnt lgkmcnt(3)
	v_mfma_f32_32x32x16_bf16 v[96:111], v[126:129], v[144:147], 0
	ds_read_b128 v[126:129], v161 offset:13376
	s_waitcnt lgkmcnt(3)
	v_mfma_f32_32x32x16_bf16 v[80:95], v[130:133], v[144:147], 0
	ds_read_b128 v[130:133], v161 offset:17984
	s_waitcnt lgkmcnt(3)
	v_mfma_f32_32x32x16_bf16 v[96:111], v[164:167], v[148:151], v[96:111]
	ds_read_b128 v[164:167], v161 offset:13408
	s_waitcnt lgkmcnt(3)
	v_mfma_f32_32x32x16_bf16 v[80:95], v[10:13], v[148:151], v[80:95]
	ds_read_b128 v[10:13], v161 offset:18016
	s_waitcnt lgkmcnt(3)
	v_mfma_f32_32x32x16_bf16 v[96:111], v[126:129], v[152:155], v[96:111]
	s_waitcnt lgkmcnt(2)
	v_mfma_f32_32x32x16_bf16 v[80:95], v[130:133], v[152:155], v[80:95]
	s_waitcnt lgkmcnt(1)
	v_mfma_f32_32x32x16_bf16 v[96:111], v[164:167], v[156:159], v[96:111]
	s_waitcnt lgkmcnt(0)
	v_mfma_f32_32x32x16_bf16 v[80:95], v[10:13], v[156:159], v[80:95]
	v_sub_u32_e32 v163, s43, v205
	v_cvt_f32_i32_e32 v163, v163
	v_mul_f32_e32 v134, v186, v163
	v_cndmask_b32_e32 v134, v225, v134, vcc
	s_nop 7
	v_fma_f32 v96, v96, s84, v140
	v_fma_f32 v97, v97, s84, v160
	v_fma_f32 v98, v98, s84, v170
	v_fma_f32 v99, v99, s84, v171
	v_fma_f32 v100, v100, s84, v176
	v_fma_f32 v101, v101, s84, v177
	v_fma_f32 v102, v102, s84, v187
	v_fma_f32 v103, v103, s84, v188
	v_fma_f32 v104, v104, s84, v189
	v_fma_f32 v105, v105, s84, v190
	v_fma_f32 v106, v106, s84, v191
	v_fma_f32 v107, v107, s84, v192
	v_fma_f32 v108, v108, s84, v193
	v_fma_f32 v109, v109, s84, v194
	v_fma_f32 v110, v110, s84, v195
	v_fma_f32 v111, v111, s84, v196
	v_fma_f32 v80, v80, s84, v197
	v_fma_f32 v81, v81, s84, v198
	v_fma_f32 v82, v82, s84, v199
	v_fma_f32 v83, v83, s84, v207
	v_fma_f32 v84, v84, s84, v210
	v_fma_f32 v85, v85, s84, v211
	v_fma_f32 v86, v86, s84, v212
	v_fma_f32 v87, v87, s84, v213
	v_fma_f32 v88, v88, s84, v233
	v_fma_f32 v89, v89, s84, v234
	v_fma_f32 v90, v90, s84, v235
	v_fma_f32 v91, v91, s84, v236
	v_fma_f32 v92, v92, s84, v237
	v_fma_f32 v93, v93, s84, v238
	v_fma_f32 v94, v94, s84, v239
	v_fma_f32 v95, v95, s84, v248
	s_add_i32 s24, s43, 63
	s_cmp_gt_i32 s24, s52
	s_cbranch_scc1 .Lsel_mask1
